# XCD-local barriers at all in-layer seams: mixer work units remapped so each XCD class owns one batch; one full barrier after the prologue and one before the final norm
# speedup vs baseline: 1.0628x; 1.0213x over previous
; DI f32x4 mfma16(bf16x8 a, bf16x8 b, f32x4 c) { return __builtin_amdgcn_mfma_f32_16x16x32_bf16(a, b, c, 0, 0, 0); }
; __global__ void __launch_bounds__(512, 2) fwd_megakernel(Args args) {
;     ...
;                 for (int rb = gw; rb < MTOK / 16; rb += NGW) {
;                     const bf16* xa = xb + (size_t)(rb * 16 + r16) * DM + q4 * 8;
;                     f32x4 acc = (f32x4){0.f, 0.f, 0.f, 0.f};
; #pragma unroll 16
;                     for (int ks = 0; ks < 32; ++ks) acc = mfma16(*(const bf16x8*)(xa + ks * 32), *(const bf16x8*)(wdt + ks * 32), acc);
.LBB0_342:
	v_readlane_b32 s2, v252, 0
	v_readlane_b32 s3, v251, 0
	s_and_b32 s4, s3, 7
	s_lshl_b32 s4, s4, 5
	s_lshr_b32 s3, s3, 3
	s_add_i32 s3, s3, s4
	s_lshl_b32 s3, s3, 3
	s_add_i32 s3, s3, s2
	s_lshl_b32 s2, s3, 15
	s_add_u32 s4, s80, 0x6000000
	s_addc_u32 s5, s81, 0
	s_add_u32 s4, s4, s2
	s_addc_u32 s5, s5, 0
	v_readlane_b32 s6, v255, 29
	v_readlane_b32 s7, v255, 30
	s_sub_u32 s6, s6, 0x200
	s_subb_u32 s7, s7, 0
	v_readlane_b32 s8, v253, 58
	s_mul_i32 s8, s8, 0x30000
	s_add_u32 s8, s8, 0x5980000
	s_lshl_b32 s2, s3, 8
	s_add_u32 s2, s2, s8
	s_add_u32 s8, s80, s2
	s_addc_u32 s9, s81, 0
	s_lshl_b32 s2, s3, 9
	s_add_u32 s10, s80, 0x500000
	s_addc_u32 s11, s81, 0
	s_add_u32 s10, s10, s2
	s_addc_u32 s11, s11, 0
	v_and_b32_e32 v20, 15, v195
	v_bfe_u32 v21, v195, 4, 2
	v_lshlrev_b32_e32 v22, 11, v20
	v_lshl_add_u32 v22, v21, 4, v22
	v_lshlrev_b32_e32 v23, 6, v21
	v_lshlrev_b32_e32 v24, 7, v21
	v_lshl_add_u32 v24, v20, 2, v24
	global_load_dwordx4 v[0:3], v23, s[8:9] offset:0
	global_load_dwordx4 v[4:7], v23, s[8:9] offset:16
	global_load_dwordx4 v[8:11], v23, s[8:9] offset:32
	global_load_dwordx4 v[12:15], v23, s[8:9] offset:48
	global_load_dwordx4 v[116:119], v22, s[4:5] offset:0
	global_load_dwordx4 v[132:135], v22, s[6:7] offset:0
	global_load_dwordx4 v[120:123], v22, s[4:5] offset:64
	global_load_dwordx4 v[136:139], v22, s[6:7] offset:64
	global_load_dwordx4 v[124:127], v22, s[4:5] offset:128
	global_load_dwordx4 v[140:143], v22, s[6:7] offset:128
	global_load_dwordx4 v[128:131], v22, s[4:5] offset:192
	global_load_dwordx4 v[144:147], v22, s[6:7] offset:192
	global_load_dwordx4 v[148:151], v22, s[4:5] offset:256
	global_load_dwordx4 v[164:167], v22, s[6:7] offset:256
	global_load_dwordx4 v[152:155], v22, s[4:5] offset:320
	global_load_dwordx4 v[168:171], v22, s[6:7] offset:320
	global_load_dwordx4 v[156:159], v22, s[4:5] offset:384
	global_load_dwordx4 v[172:175], v22, s[6:7] offset:384
	global_load_dwordx4 v[160:163], v22, s[4:5] offset:448
	global_load_dwordx4 v[176:179], v22, s[6:7] offset:448
	s_waitcnt vmcnt(8)
	v_mfma_f32_16x16x32_bf16 v[16:19], v[116:119], v[132:135], 0
	v_mfma_f32_16x16x32_bf16 v[16:19], v[120:123], v[136:139], v[16:19]
	v_mfma_f32_16x16x32_bf16 v[16:19], v[124:127], v[140:143], v[16:19]
	v_mfma_f32_16x16x32_bf16 v[16:19], v[128:131], v[144:147], v[16:19]
	global_load_dwordx4 v[116:119], v22, s[4:5] offset:512
	global_load_dwordx4 v[132:135], v22, s[6:7] offset:512
	global_load_dwordx4 v[120:123], v22, s[4:5] offset:576
	global_load_dwordx4 v[136:139], v22, s[6:7] offset:576
	global_load_dwordx4 v[124:127], v22, s[4:5] offset:640
	global_load_dwordx4 v[140:143], v22, s[6:7] offset:640
	global_load_dwordx4 v[128:131], v22, s[4:5] offset:704
	global_load_dwordx4 v[144:147], v22, s[6:7] offset:704
	s_waitcnt vmcnt(8)
	v_mfma_f32_16x16x32_bf16 v[16:19], v[148:151], v[164:167], v[16:19]
	v_mfma_f32_16x16x32_bf16 v[16:19], v[152:155], v[168:171], v[16:19]
	v_mfma_f32_16x16x32_bf16 v[16:19], v[156:159], v[172:175], v[16:19]
	v_mfma_f32_16x16x32_bf16 v[16:19], v[160:163], v[176:179], v[16:19]
	global_load_dwordx4 v[148:151], v22, s[4:5] offset:768
	global_load_dwordx4 v[164:167], v22, s[6:7] offset:768
	global_load_dwordx4 v[152:155], v22, s[4:5] offset:832
	global_load_dwordx4 v[168:171], v22, s[6:7] offset:832
	global_load_dwordx4 v[156:159], v22, s[4:5] offset:896
	global_load_dwordx4 v[172:175], v22, s[6:7] offset:896
	global_load_dwordx4 v[160:163], v22, s[4:5] offset:960
	global_load_dwordx4 v[176:179], v22, s[6:7] offset:960
	s_waitcnt vmcnt(8)
	v_mfma_f32_16x16x32_bf16 v[16:19], v[116:119], v[132:135], v[16:19]
	v_mfma_f32_16x16x32_bf16 v[16:19], v[120:123], v[136:139], v[16:19]
	v_mfma_f32_16x16x32_bf16 v[16:19], v[124:127], v[140:143], v[16:19]
	v_mfma_f32_16x16x32_bf16 v[16:19], v[128:131], v[144:147], v[16:19]
	global_load_dwordx4 v[116:119], v22, s[4:5] offset:1024
	global_load_dwordx4 v[132:135], v22, s[6:7] offset:1024
	global_load_dwordx4 v[120:123], v22, s[4:5] offset:1088
	global_load_dwordx4 v[136:139], v22, s[6:7] offset:1088
	global_load_dwordx4 v[124:127], v22, s[4:5] offset:1152
	global_load_dwordx4 v[140:143], v22, s[6:7] offset:1152
	global_load_dwordx4 v[128:131], v22, s[4:5] offset:1216
	global_load_dwordx4 v[144:147], v22, s[6:7] offset:1216
	s_waitcnt vmcnt(8)
; DI f32x4 mfma16(bf16x8 a, bf16x8 b, f32x4 c) { return __builtin_amdgcn_mfma_f32_16x16x32_bf16(a, b, c, 0, 0, 0); }
; DI float row_rstd(const float* ssq, unsigned row) { return rstd4(*(const f32x4*)(ssq + row * 4u)); }
; #define GRID_SYNC() do { XcdBarrier b_; b_.bar = (unsigned*)(args.ws + WS_BAR); b_.x = xb_xcc_id(); b_.st = (volatile LAS unsigned*)(lds + 147440); xcd_barrier(b_); } while (0)
; __global__ void __launch_bounds__(512, 2) fwd_megakernel(Args args) {
;     ...
;                     for (int ks = 0; ks < 32; ++ks) acc = mfma16(*(const bf16x8*)(xa + ks * 32), *(const bf16x8*)(wdt + ks * 32), acc);
;                     if (r16 < 8) {
; #pragma unroll
;                         for (int j = 0; j < 4; ++j) { const unsigned row = rb * 16 + q4 * 4 + j; dtraw[row * 8u + r16] = acc[j] * row_rstd(ssq_in, row); }
;                     }
;                 }
;             }
;             GRID_SYNC();
	v_mfma_f32_16x16x32_bf16 v[16:19], v[148:151], v[164:167], v[16:19]
	v_mfma_f32_16x16x32_bf16 v[16:19], v[152:155], v[168:171], v[16:19]
	v_mfma_f32_16x16x32_bf16 v[16:19], v[156:159], v[172:175], v[16:19]
	v_mfma_f32_16x16x32_bf16 v[16:19], v[160:163], v[176:179], v[16:19]
	global_load_dwordx4 v[148:151], v22, s[4:5] offset:1280
	global_load_dwordx4 v[164:167], v22, s[6:7] offset:1280
	global_load_dwordx4 v[152:155], v22, s[4:5] offset:1344
	global_load_dwordx4 v[168:171], v22, s[6:7] offset:1344
	global_load_dwordx4 v[156:159], v22, s[4:5] offset:1408
	global_load_dwordx4 v[172:175], v22, s[6:7] offset:1408
	global_load_dwordx4 v[160:163], v22, s[4:5] offset:1472
	global_load_dwordx4 v[176:179], v22, s[6:7] offset:1472
	s_waitcnt vmcnt(8)
	v_mfma_f32_16x16x32_bf16 v[16:19], v[116:119], v[132:135], v[16:19]
	v_mfma_f32_16x16x32_bf16 v[16:19], v[120:123], v[136:139], v[16:19]
	v_mfma_f32_16x16x32_bf16 v[16:19], v[124:127], v[140:143], v[16:19]
	v_mfma_f32_16x16x32_bf16 v[16:19], v[128:131], v[144:147], v[16:19]
	global_load_dwordx4 v[116:119], v22, s[4:5] offset:1536
	global_load_dwordx4 v[132:135], v22, s[6:7] offset:1536
	global_load_dwordx4 v[120:123], v22, s[4:5] offset:1600
	global_load_dwordx4 v[136:139], v22, s[6:7] offset:1600
	global_load_dwordx4 v[124:127], v22, s[4:5] offset:1664
	global_load_dwordx4 v[140:143], v22, s[6:7] offset:1664
	global_load_dwordx4 v[128:131], v22, s[4:5] offset:1728
	global_load_dwordx4 v[144:147], v22, s[6:7] offset:1728
	s_waitcnt vmcnt(8)
	v_mfma_f32_16x16x32_bf16 v[16:19], v[148:151], v[164:167], v[16:19]
	v_mfma_f32_16x16x32_bf16 v[16:19], v[152:155], v[168:171], v[16:19]
	v_mfma_f32_16x16x32_bf16 v[16:19], v[156:159], v[172:175], v[16:19]
	v_mfma_f32_16x16x32_bf16 v[16:19], v[160:163], v[176:179], v[16:19]
	global_load_dwordx4 v[148:151], v22, s[4:5] offset:1792
	global_load_dwordx4 v[164:167], v22, s[6:7] offset:1792
	global_load_dwordx4 v[152:155], v22, s[4:5] offset:1856
	global_load_dwordx4 v[168:171], v22, s[6:7] offset:1856
	global_load_dwordx4 v[156:159], v22, s[4:5] offset:1920
	global_load_dwordx4 v[172:175], v22, s[6:7] offset:1920
	global_load_dwordx4 v[160:163], v22, s[4:5] offset:1984
	global_load_dwordx4 v[176:179], v22, s[6:7] offset:1984
	s_waitcnt vmcnt(8)
	v_mfma_f32_16x16x32_bf16 v[16:19], v[116:119], v[132:135], v[16:19]
	v_mfma_f32_16x16x32_bf16 v[16:19], v[120:123], v[136:139], v[16:19]
	v_mfma_f32_16x16x32_bf16 v[16:19], v[124:127], v[140:143], v[16:19]
	v_mfma_f32_16x16x32_bf16 v[16:19], v[128:131], v[144:147], v[16:19]
	s_waitcnt vmcnt(0)
	v_mfma_f32_16x16x32_bf16 v[16:19], v[148:151], v[164:167], v[16:19]
	v_mfma_f32_16x16x32_bf16 v[16:19], v[152:155], v[168:171], v[16:19]
	v_mfma_f32_16x16x32_bf16 v[16:19], v[156:159], v[172:175], v[16:19]
	v_mfma_f32_16x16x32_bf16 v[16:19], v[160:163], v[176:179], v[16:19]
	v_mov_b32_e32 v25, 0x358637bd
	v_cmp_gt_u32_e64 s[2:3], 8, v20
	s_nop 7
	v_add_f32_e32 v0, v0, v1
	v_add_f32_e32 v2, v2, v3
	v_add_f32_e32 v0, v0, v2
	v_fmamk_f32 v0, v0, 0x3a800000, v25
	v_rsq_f32_e32 v0, v0
	v_add_f32_e32 v4, v4, v5
	v_add_f32_e32 v6, v6, v7
	v_add_f32_e32 v4, v4, v6
	v_fmamk_f32 v4, v4, 0x3a800000, v25
	v_rsq_f32_e32 v4, v4
	v_add_f32_e32 v8, v8, v9
	v_add_f32_e32 v10, v10, v11
	v_add_f32_e32 v8, v8, v10
	v_fmamk_f32 v8, v8, 0x3a800000, v25
	v_rsq_f32_e32 v8, v8
	v_add_f32_e32 v12, v12, v13
	v_add_f32_e32 v14, v14, v15
	v_add_f32_e32 v12, v12, v14
	v_fmamk_f32 v12, v12, 0x3a800000, v25
	v_rsq_f32_e32 v12, v12
	s_nop 0
	v_mul_f32_e32 v16, v16, v0
	v_mul_f32_e32 v17, v17, v4
	v_mul_f32_e32 v18, v18, v8
	v_mul_f32_e32 v19, v19, v12
	s_mov_b64 exec, s[2:3]
	global_store_dword v24, v16, s[10:11] offset:0
	global_store_dword v24, v17, s[10:11] offset:32
	global_store_dword v24, v18, s[10:11] offset:64
	global_store_dword v24, v19, s[10:11] offset:96
	s_mov_b64 exec, -1
.LBB0_349:
	s_getreg_b32 s2, hwreg(HW_REG_XCC_ID, 0, 4)
	s_waitcnt vmcnt(0)
	s_waitcnt vmcnt(0) lgkmcnt(0)
	s_barrier
	s_and_saveexec_b64 s[4:5], s[76:77]
	s_cbranch_execz .LBB0_401
	v_mov_b32_e32 v0, 0x23ff8
	ds_read_b32 v2, v0
	s_waitcnt lgkmcnt(0)
	v_readfirstlane_b32 s3, v2
	s_cmp_eq_u32 s3, 1
	s_cbranch_scc1 .Lfb4_fast
	s_branch .Lfb4_slow

; #define PHASE_IDS() const int tid = opaque_tid(), lane = tid & 63, r16 = lane & 15, q4 = lane >> 4; (void)r16; (void)q4; (void)tid
; __global__ void __launch_bounds__(512, 2) fwd_megakernel(Args args) {
;     ...
;             for (int unit = bid; unit < BATCH * NCH * 2; unit += G) {
;                 PHASE_IDS();
;                 const int g2 = unit & 1, c = (unit >> 1) & 31, b = unit >> 6;
;                 const size_t grow0 = (size_t)b * SEQ + c * 128;
.LBB0_401:
	s_or_b64 exec, exec, s[4:5]
	s_and_b64 vcc, exec, s[26:27]
	s_and_b32 s22, s54, 7
	s_lshl_b32 s22, s22, 5
	s_lshr_b32 s2, s54, 3
	s_add_i32 s22, s22, s2
	s_lshl_b32 s22, s22, 1
	s_waitcnt lgkmcnt(0)
	s_barrier
	s_cbranch_vccz .LBB0_407

; #define GRID_SYNC() do { XcdBarrier b_; b_.bar = (unsigned*)(args.ws + WS_BAR); b_.x = xb_xcc_id(); b_.st = (volatile LAS unsigned*)(lds + 147440); xcd_barrier(b_); } while (0)
; __global__ void __launch_bounds__(512, 2) fwd_megakernel(Args args) {
;     ...
;                 __syncthreads();
;             }
;             GRID_SYNC();
.LBB0_403:
	s_getreg_b32 s2, hwreg(HW_REG_XCC_ID, 0, 4)
	s_waitcnt vmcnt(0)
	s_barrier
	s_and_saveexec_b64 s[4:5], s[76:77]
	s_cbranch_execz .LBB0_867
	v_mov_b32_e32 v0, 0x23ff8
	ds_read_b32 v2, v0
	s_waitcnt lgkmcnt(0)
	v_readfirstlane_b32 s3, v2
	s_cmp_eq_u32 s3, 1
	s_cbranch_scc1 .Lfb5_fast
	s_branch .Lfb5_slow

; __global__ void __launch_bounds__(512, 2) fwd_megakernel(Args args) {
;     ...
;             for (int unit = bid; unit < BATCH * NCH * 2; unit += G) {
.LBB0_406:
	s_or_b64 exec, exec, s[4:5]
	s_add_i32 s22, s22, 1
	s_bitcmp0_b32 s22, 0
	s_barrier
	s_cbranch_scc1 .LBB0_402

; #define LAS __attribute__((address_space(3)))
; #define PHASE_IDS() const int tid = opaque_tid(), lane = tid & 63, r16 = lane & 15, q4 = lane >> 4; (void)r16; (void)q4; (void)tid
; __global__ void __launch_bounds__(512, 2) fwd_megakernel(Args args) {
;     ...
;             for (int unit = bid; unit < BATCH * NCH; unit += G) {
;                 PHASE_IDS();
;                 const int nb = unit & 31, b = unit >> 5;
;                 const size_t grow0 = (size_t)b * SEQ + nb * 128;
;                 LAS bf16* Ks = (LAS bf16*)lds; LAS bf16* VT = (LAS bf16*)(lds + 36864); LAS bf16* Ps = (LAS bf16*)(lds + 72704) + wave * (16 * 168);
;                 LAS float* s_bias = (LAS float*)(lds + 115712);
;                 s_bias[tid] = args.in[14][T5_BUCKET[tid & 127] * 4 + (tid >> 7)];
;                 for (int it = tid; it < 64 * 24; it += 512) { const int d = it / 24, j = 256 + it % 24; VT[d * 280 + j] = 0; }
;                 f32x4 og[4][4]; float ssr[4] = {0.f, 0.f, 0.f, 0.f};
; #pragma unroll
.LBB0_448:
	s_waitcnt vmcnt(0) lgkmcnt(0)
	v_readlane_b32 s3, v252, 0
	s_mov_b32 s50, 0x3e000000
	s_and_b32 s51, s2, 7
	s_lshl_b32 s51, s51, 5
	s_lshr_b32 s28, s2, 3
	s_add_i32 s51, s51, s28
	s_and_b32 s28, s51, 31
	s_sub_i32 s29, 8, s3
	s_cmp_eq_u32 s28, 0
	s_cselect_b32 s29, s29, 0
	s_mul_i32 s30, s51, 0xb0000
	s_add_u32 s8, s80, 0x15000000
	s_addc_u32 s9, s81, 0
	s_add_u32 s8, s8, s30
	s_addc_u32 s9, s9, 0
	s_lshl_b32 s30, s51, 18
	s_add_u32 s10, s80, 0xa000400
	s_addc_u32 s11, s81, 0
	s_add_u32 s10, s10, s30
	s_addc_u32 s11, s11, 0
	s_lshl_b32 s30, s51, 9
	s_add_u32 s12, s80, 0x400000
	s_addc_u32 s13, s81, 0
	s_add_u32 s12, s12, s30
	s_addc_u32 s13, s13, 0
	v_readlane_b32 s14, v251, 35
	v_readlane_b32 s15, v251, 36
	v_readlane_b32 s30, v253, 58
	s_lshl_b32 s30, s30, 1
	s_add_u32 s14, s14, s30
	s_addc_u32 s15, s15, 0
	s_load_dwordx4 s[36:39], s[14:15], 0x0
	v_readlane_b32 s16, v251, 37
	v_readlane_b32 s17, v251, 38
	s_sub_u32 s18, s8, 0xaf200
	s_subb_u32 s19, s9, 0
	s_add_u32 s20, s18, 0x58000
	s_addc_u32 s21, s19, 0
	s_add_u32 s22, s20, 0x58000
	s_addc_u32 s23, s21, 0
	s_add_u32 s24, s22, 0x58000
	s_addc_u32 s25, s23, 0
	v_and_b32_e32 v160, 15, v195
	v_bfe_u32 v161, v195, 4, 2
	v_lshl_add_u32 v175, s3, 4, v160
	v_mul_u32_u24_e32 v162, 0x90, v175
	v_lshl_add_u32 v162, v161, 4, v162
	v_and_b32_e32 v176, 63, v195
	v_bfe_u32 v177, v176, 2, 2
	v_and_b32_e32 v178, 3, v176
	v_lshl_add_u32 v177, v161, 2, v177
	v_lshl_add_u32 v177, s3, 4, v177
	v_mul_u32_u24_e32 v163, 0x90, v177
	v_lshl_add_u32 v163, v178, 3, v163
	v_add_u32_e32 v163, 0x9000, v163
	v_lshlrev_b32_e32 v164, 2, v160
	v_lshlrev_b32_e32 v177, 4, v161
	v_sub_u32_e32 v164, v164, v177
	v_add_u32_e32 v164, 0x128f4, v164
	v_lshlrev_b32_e32 v165, 11, v175
	v_lshl_add_u32 v165, v161, 3, v165
	v_lshlrev_b32_e32 v166, 2, v175
	v_lshrrev_b32_e32 v177, 3, v195
	v_and_b32_e32 v178, 7, v195
	v_mul_u32_u24_e32 v167, 0x1600, v177
	v_lshl_add_u32 v167, v178, 4, v167
	v_mul_u32_u24_e32 v168, 0x90, v177
	v_lshl_add_u32 v168, v178, 4, v168
	v_mul_u32_u24_e32 v169, 0x1600, v175
	v_lshl_add_u32 v169, v161, 4, v169
	v_add_u32_e32 v169, 0xc00, v169
	v_xor_b32_e32 v173, 16, v176
	v_lshlrev_b32_e32 v173, 2, v173
	v_xor_b32_e32 v174, 32, v176
	v_lshlrev_b32_e32 v174, 2, v174
	v_lshlrev_b32_e32 v177, 2, v161
	v_add_u32_e32 v178, 0, v177
	v_cmp_le_u32_e64 s[40:41], v178, v160
	v_add_u32_e32 v178, 1, v177
	v_cmp_le_u32_e64 s[42:43], v178, v160
	v_add_u32_e32 v178, 2, v177
	v_cmp_le_u32_e64 s[44:45], v178, v160
	v_add_u32_e32 v178, 3, v177
	v_cmp_le_u32_e64 s[46:47], v178, v160
	v_cmp_eq_u32_e64 s[48:49], 0, v161
	s_getpc_b64 s[4:5]
	s_add_u32 s4, s4, _ZL9T5_BUCKET@rel32@lo+4
	s_addc_u32 s5, s5, _ZL9T5_BUCKET@rel32@hi+12
	v_and_b32_e32 v177, 0x7f, v195
	global_load_ubyte v179, v177, s[4:5]
	global_load_dwordx4 v[0:3], v169, s[8:9] offset:0
	global_load_dwordx4 v[4:7], v169, s[8:9] offset:64
	global_load_dwordx4 v[8:11], v169, s[8:9] offset:128
	global_load_dwordx4 v[12:15], v169, s[8:9] offset:192
	global_load_dwordx4 v[16:19], v169, s[8:9] offset:256
	global_load_dwordx4 v[20:23], v169, s[8:9] offset:320
	global_load_dwordx4 v[24:27], v169, s[8:9] offset:384
	global_load_dwordx4 v[28:31], v169, s[8:9] offset:448
	v_mov_b32_e32 v180, 0
	v_mov_b32_e32 v181, 0
	v_mov_b32_e32 v182, 0
	v_mov_b32_e32 v183, 0
	s_movk_i32 s30, 0x90
	v_cmp_gt_u32_e64 s[6:7], s30, v195
	v_lshlrev_b32_e32 v177, 4, v195
	v_add_u32_e32 v177, 73728, v177
	s_and_saveexec_b64 s[34:35], s[6:7]
	ds_write_b128 v177, v[180:183]
	s_mov_b64 exec, s[34:35]
	s_cmp_eq_u32 s28, 0
	s_cbranch_scc1 .Lm1b_st0r0_first
	global_load_dwordx4 v[120:123], v167, s[18:19] offset:0
	global_load_dwordx4 v[124:127], v167, s[18:19] offset:256
	global_load_dwordx4 v[128:131], v167, s[20:21] offset:0
	global_load_dwordx4 v[132:135], v167, s[20:21] offset:256
	global_load_dwordx4 v[136:139], v167, s[22:23] offset:0
	global_load_dwordx4 v[140:143], v167, s[22:23] offset:256
	global_load_dwordx4 v[144:147], v167, s[24:25] offset:0
	global_load_dwordx4 v[148:151], v167, s[24:25] offset:256
	s_branch .Lm1b_st0r0_ld

; #define LAS __attribute__((address_space(3)))
; #define PHASE_IDS() const int tid = opaque_tid(), lane = tid & 63, r16 = lane & 15, q4 = lane >> 4; (void)r16; (void)q4; (void)tid
; __global__ void __launch_bounds__(512, 2) fwd_megakernel(Args args) {
;     ...
;             for (int unit = bid; unit < BATCH * NCH; unit += G) {
;                 PHASE_IDS();
;                 const int c = unit & 31, b = unit >> 5;
;                 const size_t grow0 = (size_t)b * SEQ + c * 128;
;                 LAS bf16* vnT = (LAS bf16*)lds;
;                 LAS bf16* Us = (LAS bf16*)(lds + 69632);
;                 const int l = tid >> 2, sub = tid & 3;
.LBB0_800:
	s_and_b32 s12, s54, 7
	s_lshl_b32 s12, s12, 5
	s_lshr_b32 s2, s54, 3
	s_add_i32 s12, s12, s2
	s_lshl_b32 s2, s12, 7
	s_mov_b32 s6, 0x800000
	s_branch .LBB0_802

; #define PHASE_IDS() const int tid = opaque_tid(), lane = tid & 63, r16 = lane & 15, q4 = lane >> 4; (void)r16; (void)q4; (void)tid
; __global__ void __launch_bounds__(512, 2) fwd_megakernel(Args args) {
;     ...
;             { PHASE_IDS();
;             for (int e = bid * 512 + tid; e < BATCH * 8 * 2048; e += G * 512) {
;                 const int i4 = e & 2047, h = (e >> 11) & 7, b = e >> 14;
;                 f32x4 carry = (f32x4){0.f, 0.f, 0.f, 0.f};
.LBB0_867:
	s_or_b64 exec, exec, s[4:5]
	v_readlane_b32 s2, v251, 0
	s_and_b32 s3, s2, 7
	s_lshl_b32 s3, s3, 5
	s_lshr_b32 s2, s2, 3
	s_add_i32 s2, s2, s3
	s_lshl_b32 s2, s2, 9
	s_waitcnt lgkmcnt(0)
	s_barrier
	v_mov_b32 v0, v195
	s_nop 0
	v_add_u32_e32 v12, s2, v0
	s_mov_b32 s2, 0x20000
	v_cmp_gt_i32_e32 vcc, s2, v12
	s_and_saveexec_b64 s[4:5], vcc
	s_cbranch_execz .LBB0_872
	s_mov_b64 s[6:7], 0

; #define GRID_SYNC() do { XcdBarrier b_; b_.bar = (unsigned*)(args.ws + WS_BAR); b_.x = xb_xcc_id(); b_.st = (volatile LAS unsigned*)(lds + 147440); xcd_barrier(b_); } while (0)
; __global__ void __launch_bounds__(512, 2) fwd_megakernel(Args args) {
;     ...
;             } }
;             GRID_SYNC();
.LBB0_872:
	s_or_b64 exec, exec, s[4:5]
	s_getreg_b32 s2, hwreg(HW_REG_XCC_ID, 0, 4)
	s_waitcnt vmcnt(0)
	s_barrier
	s_and_saveexec_b64 s[4:5], s[76:77]
	s_cbranch_execz .LBB0_924
	v_mov_b32_e32 v0, 0x23ff8
	ds_read_b32 v2, v0
	s_waitcnt lgkmcnt(0)
	v_readfirstlane_b32 s3, v2
	s_cmp_eq_u32 s3, 1
	s_cbranch_scc1 .Lfb6_fast
	s_branch .Lfb6_slow

; #define PHASE_IDS() const int tid = opaque_tid(), lane = tid & 63, r16 = lane & 15, q4 = lane >> 4; (void)r16; (void)q4; (void)tid
; __global__ void __launch_bounds__(512, 2) fwd_megakernel(Args args) {
;     ...
;             for (int unit = bid; unit < BATCH * NCH * 2; unit += G) {
;                 PHASE_IDS();
;                 const int g2 = unit & 1, c = (unit >> 1) & 31, b = unit >> 6;
;                 const size_t grow0 = (size_t)b * SEQ + c * 128;
.LBB0_924:
	s_or_b64 exec, exec, s[4:5]
	v_readlane_b32 s28, v253, 17
	s_and_b64 vcc, exec, s[26:27]
	v_readlane_b32 s29, v253, 18
	s_and_b32 s83, s54, 7
	s_lshl_b32 s83, s83, 5
	s_lshr_b32 s2, s54, 3
	s_add_i32 s83, s83, s2
	s_lshl_b32 s83, s83, 1
	s_waitcnt lgkmcnt(0)
	s_barrier
	s_cbranch_vccz .LBB0_929

; DI u32x4 pack8(const float (&v)[8]) { u32x4 r; r.x = pk2(v[0], v[1]); r.y = pk2(v[2], v[3]); r.z = pk2(v[4], v[5]); r.w = pk2(v[6], v[7]); return r; }
; __global__ void __launch_bounds__(512, 2) fwd_megakernel(Args args) {
;     ...
;                 for (int r = 0; r < 4; ++r) { const int m = min(m0 + r * NGW, MTOK - 1);
;                     sv[r][0] = *(const f32x4*)(mss_g + (size_t)m * 4); sv[r][1] = *(const f32x4*)(mss_g + ((size_t)MTOK + m) * 4); sv[r][2] = (f32x4){mss_a[m], mss_a[(size_t)MTOK + m], mss_a[(size_t)2 * MTOK + m], mss_a[(size_t)3 * MTOK + m]};
;                     yv[r][0] = *(const u32x4*)(Yg + (size_t)m * DM + colA); yv[r][1] = *(const u32x4*)(Yg + (size_t)m * DM + 512 + (lane & 31) * 8); }
;                 float nwA[8], nwB[8];
;                 { const float* p = args.in[12] + layer * 512 + colA;
; #pragma unroll
;                   for (int i = 0; i < 8; ++i) nwA[i] = p[i];
;                   const float* q = args.in[15] + layer * 256 + (lane & 31) * 8;
; #pragma unroll
;                   for (int i = 0; i < 8; ++i) nwB[i] = q[i]; }
; #pragma unroll
;                 for (int r = 0; r < 4; ++r) { const int m = m0 + r * NGW; if (m < MTOK) {
;                     const f32x4 s0 = sv[r][0], s1 = sv[r][1], s2 = sv[r][2];
;                     const float r_ssd = rsqrtf((((s0.x + s0.y) + (s0.z + s0.w)) + ((s1.x + s1.y) + (s1.z + s1.w))) * (1.f / 512.f) + EPS);
;                     const float r_att = rsqrtf(((s2.x + s2.y) + (s2.z + s2.w)) * (1.f / 256.f) + EPS);
;                     float v[8]; unpack8(yv[r][0], v);
; #pragma unroll
;                     for (int i = 0; i < 8; ++i) v[i] = v[i] * r_ssd * nwA[i];
;                     *(u32x4*)(ycat + (size_t)m * DM + colA) = pack8(v);
.Lm4f:
	s_waitcnt vmcnt(0) lgkmcnt(0)
	s_barrier
	v_readlane_b32 s2, v252, 0
	v_readlane_b32 s3, v251, 0
	s_and_b32 s29, s3, 7
	s_lshl_b32 s29, s29, 5
	s_lshr_b32 s3, s3, 3
	s_add_i32 s3, s3, s29
	s_lshl_b32 s3, s3, 7
	s_lshl_b32 s29, s2, 4
	s_add_i32 s3, s3, s29
	s_lshl_b32 s29, s3, 11
	s_add_u32 s4, s80, 0xa000000
	s_addc_u32 s5, s81, 0
	s_add_u32 s4, s4, s29
	s_addc_u32 s5, s5, 0
	s_add_u32 s6, s80, 0xe000000
	s_addc_u32 s7, s81, 0
	s_add_u32 s6, s6, s29
	s_addc_u32 s7, s7, 0
	s_lshl_b32 s29, s3, 4
	s_add_u32 s8, s80, 0x300000
	s_addc_u32 s9, s81, 0
	s_add_u32 s8, s8, s29
	s_addc_u32 s9, s9, 0
	s_lshl_b32 s29, s3, 2
	s_add_u32 s12, s80, 0x400000
	s_addc_u32 s13, s81, 0
	s_add_u32 s12, s12, s29
	s_addc_u32 s13, s13, 0
	v_readlane_b32 s29, v253, 58
	v_readlane_b32 s30, v251, 33
	v_readlane_b32 s31, v251, 34
	s_lshl_b32 s10, s29, 8
	s_add_u32 s30, s30, s10
	s_addc_u32 s31, s31, 0
	v_readlane_b32 s34, v251, 39
	v_readlane_b32 s35, v251, 40
	s_lshl_b32 s10, s29, 7
	s_add_u32 s34, s34, s10
	s_addc_u32 s35, s35, 0
	v_and_b32_e32 v116, 63, v195
	v_and_b32_e32 v161, 15, v116
	v_bfe_u32 v162, v116, 4, 2
	v_and_b32_e32 v163, 1, v162
	v_lshlrev_b32_e32 v163, 19, v163
	v_lshl_add_u32 v163, v161, 4, v163
	global_load_dwordx4 v[134:137], v163, s[8:9]
	v_lshlrev_b32_e32 v163, 17, v162
	v_lshl_add_u32 v163, v161, 2, v163
	global_load_dword v138, v163, s[12:13]
	v_lshlrev_b32_e32 v163, 5, v116
	global_load_dwordx4 v[118:121], v163, s[30:31]
	global_load_dwordx4 v[122:125], v163, s[30:31] offset:16
	v_and_b32_e32 v164, 31, v116
	v_lshlrev_b32_e32 v164, 5, v164
	global_load_dwordx4 v[126:129], v164, s[34:35]
	global_load_dwordx4 v[130:133], v164, s[34:35] offset:16
	v_xor_b32_e32 v165, 16, v116
	v_lshlrev_b32_e32 v165, 2, v165
	v_xor_b32_e32 v166, 32, v116
	v_lshlrev_b32_e32 v166, 2, v166
	v_lshlrev_b32_e32 v117, 4, v116
	s_waitcnt vmcnt(4)
	v_add_f32_e32 v134, v134, v135
	v_add_f32_e32 v136, v136, v137
	v_add_f32_e32 v134, v134, v136
	ds_bpermute_b32 v135, v165, v134
	ds_bpermute_b32 v139, v165, v138
	s_waitcnt lgkmcnt(0)
	v_add_f32_e32 v134, v134, v135
	v_add_f32_e32 v138, v138, v139
	ds_bpermute_b32 v139, v166, v138
	v_mov_b32_e32 v167, 0x358637bd
	v_fmamk_f32 v154, v134, 0x3b000000, v167
	v_rsq_f32_e32 v154, v154
	s_waitcnt lgkmcnt(0)
	v_add_f32_e32 v138, v138, v139
	v_fmamk_f32 v160, v138, 0x3b800000, v167
	v_rsq_f32_e32 v160, v160
	s_nop 0
	v_readlane_b32 s60, v154, 0
	v_readlane_b32 s61, v154, 1
	v_readlane_b32 s62, v154, 2
	v_readlane_b32 s63, v154, 3
	v_readlane_b32 s64, v154, 4
	v_readlane_b32 s65, v154, 5
	v_readlane_b32 s66, v154, 6
	v_readlane_b32 s67, v154, 7
	v_readlane_b32 s68, v154, 8
	v_readlane_b32 s69, v154, 9
	v_readlane_b32 s70, v154, 10
	v_readlane_b32 s71, v154, 11
	v_readlane_b32 s72, v154, 12
	v_readlane_b32 s73, v154, 13
	v_readlane_b32 s74, v154, 14
	v_readlane_b32 s75, v154, 15
	s_waitcnt vmcnt(0)
	v_add_u32_e32 v169, 0, v117
	global_load_dwordx4 v[170:173], v169, s[4:5]
	v_add_u32_e32 v169, 2048, v117
	global_load_dwordx4 v[174:177], v169, s[4:5]
	v_add_u32_e32 v169, 4096, v117
	global_load_dwordx4 v[178:181], v169, s[4:5]
	v_add_u32_e32 v169, 6144, v117
	global_load_dwordx4 v[182:185], v169, s[4:5]
	s_waitcnt vmcnt(3)
	v_add_u32_e32 v169, 0, v117
	v_lshlrev_b32_e32 v142, 16, v170
	v_and_b32_e32 v143, 0xffff0000, v170
	v_lshlrev_b32_e32 v144, 16, v171
	v_and_b32_e32 v145, 0xffff0000, v171
	v_lshlrev_b32_e32 v146, 16, v172
	v_and_b32_e32 v147, 0xffff0000, v172
	v_lshlrev_b32_e32 v148, 16, v173
	v_and_b32_e32 v149, 0xffff0000, v173
	v_mul_f32_e32 v142, s60, v142
	v_mul_f32_e32 v143, s60, v143
	v_mul_f32_e32 v144, s60, v144
	v_mul_f32_e32 v145, s60, v145
	v_mul_f32_e32 v146, s60, v146
	v_mul_f32_e32 v147, s60, v147
	v_mul_f32_e32 v148, s60, v148
	v_mul_f32_e32 v149, s60, v149
	v_mul_f32_e32 v142, v142, v118
	v_mul_f32_e32 v143, v143, v119
	v_mul_f32_e32 v144, v144, v120
	v_mul_f32_e32 v145, v145, v121
	v_mul_f32_e32 v146, v146, v122
	v_mul_f32_e32 v147, v147, v123
	v_mul_f32_e32 v148, v148, v124
	v_mul_f32_e32 v149, v149, v125
	v_cvt_pk_bf16_f32 v150, v142, v143
	v_cvt_pk_bf16_f32 v151, v144, v145
	v_cvt_pk_bf16_f32 v152, v146, v147
	v_cvt_pk_bf16_f32 v153, v148, v149
	global_store_dwordx4 v169, v[150:153], s[6:7] offset:0
	s_nop 1
	s_waitcnt vmcnt(2)
	v_add_u32_e32 v169, 2048, v117
	v_lshlrev_b32_e32 v142, 16, v174
	v_and_b32_e32 v143, 0xffff0000, v174
	v_lshlrev_b32_e32 v144, 16, v175
	v_and_b32_e32 v145, 0xffff0000, v175
	v_lshlrev_b32_e32 v146, 16, v176
	v_and_b32_e32 v147, 0xffff0000, v176
	v_lshlrev_b32_e32 v148, 16, v177
	v_and_b32_e32 v149, 0xffff0000, v177
	v_mul_f32_e32 v142, s61, v142
	v_mul_f32_e32 v143, s61, v143
	v_mul_f32_e32 v144, s61, v144
	v_mul_f32_e32 v145, s61, v145
	v_mul_f32_e32 v146, s61, v146
	v_mul_f32_e32 v147, s61, v147
	v_mul_f32_e32 v148, s61, v148
	v_mul_f32_e32 v149, s61, v149
	v_mul_f32_e32 v142, v142, v118
	v_mul_f32_e32 v143, v143, v119
	v_mul_f32_e32 v144, v144, v120
	v_mul_f32_e32 v145, v145, v121
	v_mul_f32_e32 v146, v146, v122
	v_mul_f32_e32 v147, v147, v123
	v_mul_f32_e32 v148, v148, v124
	v_mul_f32_e32 v149, v149, v125
	v_cvt_pk_bf16_f32 v150, v142, v143
	v_cvt_pk_bf16_f32 v151, v144, v145
	v_cvt_pk_bf16_f32 v152, v146, v147
	v_cvt_pk_bf16_f32 v153, v148, v149
	global_store_dwordx4 v169, v[150:153], s[6:7] offset:0
	s_nop 1
	s_waitcnt vmcnt(1)
; DI u32x4 pack8(const float (&v)[8]) { u32x4 r; r.x = pk2(v[0], v[1]); r.y = pk2(v[2], v[3]); r.z = pk2(v[4], v[5]); r.w = pk2(v[6], v[7]); return r; }
; __global__ void __launch_bounds__(512, 2) fwd_megakernel(Args args) {
;     ...
;                 for (int r = 0; r < 4; ++r) { const int m = m0 + r * NGW; if (m < MTOK) {
;                     const f32x4 s0 = sv[r][0], s1 = sv[r][1], s2 = sv[r][2];
;                     const float r_ssd = rsqrtf((((s0.x + s0.y) + (s0.z + s0.w)) + ((s1.x + s1.y) + (s1.z + s1.w))) * (1.f / 512.f) + EPS);
;                     const float r_att = rsqrtf(((s2.x + s2.y) + (s2.z + s2.w)) * (1.f / 256.f) + EPS);
;                     float v[8]; unpack8(yv[r][0], v);
; #pragma unroll
;                     for (int i = 0; i < 8; ++i) v[i] = v[i] * r_ssd * nwA[i];
;                     *(u32x4*)(ycat + (size_t)m * DM + colA) = pack8(v);
	v_add_u32_e32 v169, 4096, v117
	v_lshlrev_b32_e32 v142, 16, v178
	v_and_b32_e32 v143, 0xffff0000, v178
	v_lshlrev_b32_e32 v144, 16, v179
	v_and_b32_e32 v145, 0xffff0000, v179
	v_lshlrev_b32_e32 v146, 16, v180
	v_and_b32_e32 v147, 0xffff0000, v180
	v_lshlrev_b32_e32 v148, 16, v181
	v_and_b32_e32 v149, 0xffff0000, v181
	v_mul_f32_e32 v142, s62, v142
	v_mul_f32_e32 v143, s62, v143
	v_mul_f32_e32 v144, s62, v144
	v_mul_f32_e32 v145, s62, v145
	v_mul_f32_e32 v146, s62, v146
	v_mul_f32_e32 v147, s62, v147
	v_mul_f32_e32 v148, s62, v148
	v_mul_f32_e32 v149, s62, v149
	v_mul_f32_e32 v142, v142, v118
	v_mul_f32_e32 v143, v143, v119
	v_mul_f32_e32 v144, v144, v120
	v_mul_f32_e32 v145, v145, v121
	v_mul_f32_e32 v146, v146, v122
	v_mul_f32_e32 v147, v147, v123
	v_mul_f32_e32 v148, v148, v124
	v_mul_f32_e32 v149, v149, v125
	v_cvt_pk_bf16_f32 v150, v142, v143
	v_cvt_pk_bf16_f32 v151, v144, v145
	v_cvt_pk_bf16_f32 v152, v146, v147
	v_cvt_pk_bf16_f32 v153, v148, v149
	global_store_dwordx4 v169, v[150:153], s[6:7] offset:0
	s_nop 1
	s_waitcnt vmcnt(0)
	v_add_u32_e32 v169, 6144, v117
	v_lshlrev_b32_e32 v142, 16, v182
	v_and_b32_e32 v143, 0xffff0000, v182
	v_lshlrev_b32_e32 v144, 16, v183
	v_and_b32_e32 v145, 0xffff0000, v183
	v_lshlrev_b32_e32 v146, 16, v184
	v_and_b32_e32 v147, 0xffff0000, v184
	v_lshlrev_b32_e32 v148, 16, v185
	v_and_b32_e32 v149, 0xffff0000, v185
	v_mul_f32_e32 v142, s63, v142
	v_mul_f32_e32 v143, s63, v143
	v_mul_f32_e32 v144, s63, v144
	v_mul_f32_e32 v145, s63, v145
	v_mul_f32_e32 v146, s63, v146
	v_mul_f32_e32 v147, s63, v147
	v_mul_f32_e32 v148, s63, v148
	v_mul_f32_e32 v149, s63, v149
	v_mul_f32_e32 v142, v142, v118
	v_mul_f32_e32 v143, v143, v119
	v_mul_f32_e32 v144, v144, v120
	v_mul_f32_e32 v145, v145, v121
	v_mul_f32_e32 v146, v146, v122
	v_mul_f32_e32 v147, v147, v123
	v_mul_f32_e32 v148, v148, v124
	v_mul_f32_e32 v149, v149, v125
	v_cvt_pk_bf16_f32 v150, v142, v143
	v_cvt_pk_bf16_f32 v151, v144, v145
	v_cvt_pk_bf16_f32 v152, v146, v147
	v_cvt_pk_bf16_f32 v153, v148, v149
	global_store_dwordx4 v169, v[150:153], s[6:7] offset:0
	s_nop 1
	v_add_u32_e32 v169, 8192, v117
	global_load_dwordx4 v[170:173], v169, s[4:5]
	v_add_u32_e32 v169, 10240, v117
	global_load_dwordx4 v[174:177], v169, s[4:5]
	v_add_u32_e32 v169, 12288, v117
	global_load_dwordx4 v[178:181], v169, s[4:5]
	v_add_u32_e32 v169, 14336, v117
	global_load_dwordx4 v[182:185], v169, s[4:5]
	s_waitcnt vmcnt(3)
	v_add_u32_e32 v169, 8192, v117
	v_lshlrev_b32_e32 v142, 16, v170
	v_and_b32_e32 v143, 0xffff0000, v170
	v_lshlrev_b32_e32 v144, 16, v171
	v_and_b32_e32 v145, 0xffff0000, v171
	v_lshlrev_b32_e32 v146, 16, v172
	v_and_b32_e32 v147, 0xffff0000, v172
	v_lshlrev_b32_e32 v148, 16, v173
	v_and_b32_e32 v149, 0xffff0000, v173
	v_mul_f32_e32 v142, s64, v142
	v_mul_f32_e32 v143, s64, v143
	v_mul_f32_e32 v144, s64, v144
	v_mul_f32_e32 v145, s64, v145
	v_mul_f32_e32 v146, s64, v146
	v_mul_f32_e32 v147, s64, v147
	v_mul_f32_e32 v148, s64, v148
	v_mul_f32_e32 v149, s64, v149
	v_mul_f32_e32 v142, v142, v118
	v_mul_f32_e32 v143, v143, v119
	v_mul_f32_e32 v144, v144, v120
	v_mul_f32_e32 v145, v145, v121
	v_mul_f32_e32 v146, v146, v122
	v_mul_f32_e32 v147, v147, v123
	v_mul_f32_e32 v148, v148, v124
	v_mul_f32_e32 v149, v149, v125
	v_cvt_pk_bf16_f32 v150, v142, v143
	v_cvt_pk_bf16_f32 v151, v144, v145
	v_cvt_pk_bf16_f32 v152, v146, v147
	v_cvt_pk_bf16_f32 v153, v148, v149
	global_store_dwordx4 v169, v[150:153], s[6:7] offset:0
	s_nop 1
	s_waitcnt vmcnt(2)
	v_add_u32_e32 v169, 10240, v117
	v_lshlrev_b32_e32 v142, 16, v174
	v_and_b32_e32 v143, 0xffff0000, v174
	v_lshlrev_b32_e32 v144, 16, v175
	v_and_b32_e32 v145, 0xffff0000, v175
	v_lshlrev_b32_e32 v146, 16, v176
	v_and_b32_e32 v147, 0xffff0000, v176
	v_lshlrev_b32_e32 v148, 16, v177
	v_and_b32_e32 v149, 0xffff0000, v177
	v_mul_f32_e32 v142, s65, v142
	v_mul_f32_e32 v143, s65, v143
	v_mul_f32_e32 v144, s65, v144
	v_mul_f32_e32 v145, s65, v145
	v_mul_f32_e32 v146, s65, v146
	v_mul_f32_e32 v147, s65, v147
	v_mul_f32_e32 v148, s65, v148
	v_mul_f32_e32 v149, s65, v149
	v_mul_f32_e32 v142, v142, v118
	v_mul_f32_e32 v143, v143, v119
	v_mul_f32_e32 v144, v144, v120
	v_mul_f32_e32 v145, v145, v121
	v_mul_f32_e32 v146, v146, v122
	v_mul_f32_e32 v147, v147, v123
	v_mul_f32_e32 v148, v148, v124
	v_mul_f32_e32 v149, v149, v125
	v_cvt_pk_bf16_f32 v150, v142, v143
	v_cvt_pk_bf16_f32 v151, v144, v145
	v_cvt_pk_bf16_f32 v152, v146, v147
	v_cvt_pk_bf16_f32 v153, v148, v149
	global_store_dwordx4 v169, v[150:153], s[6:7] offset:0
	s_nop 1
	s_waitcnt vmcnt(1)
	v_add_u32_e32 v169, 12288, v117
	v_lshlrev_b32_e32 v142, 16, v178
	v_and_b32_e32 v143, 0xffff0000, v178
	v_lshlrev_b32_e32 v144, 16, v179
	v_and_b32_e32 v145, 0xffff0000, v179
	v_lshlrev_b32_e32 v146, 16, v180
	v_and_b32_e32 v147, 0xffff0000, v180
	v_lshlrev_b32_e32 v148, 16, v181
	v_and_b32_e32 v149, 0xffff0000, v181
	v_mul_f32_e32 v142, s66, v142
	v_mul_f32_e32 v143, s66, v143
	v_mul_f32_e32 v144, s66, v144
	v_mul_f32_e32 v145, s66, v145
	v_mul_f32_e32 v146, s66, v146
	v_mul_f32_e32 v147, s66, v147
	v_mul_f32_e32 v148, s66, v148
	v_mul_f32_e32 v149, s66, v149
	v_mul_f32_e32 v142, v142, v118
	v_mul_f32_e32 v143, v143, v119
	v_mul_f32_e32 v144, v144, v120
	v_mul_f32_e32 v145, v145, v121
	v_mul_f32_e32 v146, v146, v122
	v_mul_f32_e32 v147, v147, v123
	v_mul_f32_e32 v148, v148, v124
	v_mul_f32_e32 v149, v149, v125
	v_cvt_pk_bf16_f32 v150, v142, v143
	v_cvt_pk_bf16_f32 v151, v144, v145
	v_cvt_pk_bf16_f32 v152, v146, v147
	v_cvt_pk_bf16_f32 v153, v148, v149
	global_store_dwordx4 v169, v[150:153], s[6:7] offset:0
	s_nop 1
	s_waitcnt vmcnt(0)
; DI u32x4 pack8(const float (&v)[8]) { u32x4 r; r.x = pk2(v[0], v[1]); r.y = pk2(v[2], v[3]); r.z = pk2(v[4], v[5]); r.w = pk2(v[6], v[7]); return r; }
; __global__ void __launch_bounds__(512, 2) fwd_megakernel(Args args) {
;     ...
;                 for (int r = 0; r < 4; ++r) { const int m = m0 + r * NGW; if (m < MTOK) {
;                     const f32x4 s0 = sv[r][0], s1 = sv[r][1], s2 = sv[r][2];
;                     const float r_ssd = rsqrtf((((s0.x + s0.y) + (s0.z + s0.w)) + ((s1.x + s1.y) + (s1.z + s1.w))) * (1.f / 512.f) + EPS);
;                     const float r_att = rsqrtf(((s2.x + s2.y) + (s2.z + s2.w)) * (1.f / 256.f) + EPS);
;                     float v[8]; unpack8(yv[r][0], v);
; #pragma unroll
;                     for (int i = 0; i < 8; ++i) v[i] = v[i] * r_ssd * nwA[i];
;                     *(u32x4*)(ycat + (size_t)m * DM + colA) = pack8(v);
	v_add_u32_e32 v169, 14336, v117
	v_lshlrev_b32_e32 v142, 16, v182
	v_and_b32_e32 v143, 0xffff0000, v182
	v_lshlrev_b32_e32 v144, 16, v183
	v_and_b32_e32 v145, 0xffff0000, v183
	v_lshlrev_b32_e32 v146, 16, v184
	v_and_b32_e32 v147, 0xffff0000, v184
	v_lshlrev_b32_e32 v148, 16, v185
	v_and_b32_e32 v149, 0xffff0000, v185
	v_mul_f32_e32 v142, s67, v142
	v_mul_f32_e32 v143, s67, v143
	v_mul_f32_e32 v144, s67, v144
	v_mul_f32_e32 v145, s67, v145
	v_mul_f32_e32 v146, s67, v146
	v_mul_f32_e32 v147, s67, v147
	v_mul_f32_e32 v148, s67, v148
	v_mul_f32_e32 v149, s67, v149
	v_mul_f32_e32 v142, v142, v118
	v_mul_f32_e32 v143, v143, v119
	v_mul_f32_e32 v144, v144, v120
	v_mul_f32_e32 v145, v145, v121
	v_mul_f32_e32 v146, v146, v122
	v_mul_f32_e32 v147, v147, v123
	v_mul_f32_e32 v148, v148, v124
	v_mul_f32_e32 v149, v149, v125
	v_cvt_pk_bf16_f32 v150, v142, v143
	v_cvt_pk_bf16_f32 v151, v144, v145
	v_cvt_pk_bf16_f32 v152, v146, v147
	v_cvt_pk_bf16_f32 v153, v148, v149
	global_store_dwordx4 v169, v[150:153], s[6:7] offset:0
	s_nop 1
	v_add_u32_e32 v169, 16384, v117
	global_load_dwordx4 v[170:173], v169, s[4:5]
	v_add_u32_e32 v169, 18432, v117
	global_load_dwordx4 v[174:177], v169, s[4:5]
	v_add_u32_e32 v169, 20480, v117
	global_load_dwordx4 v[178:181], v169, s[4:5]
	v_add_u32_e32 v169, 22528, v117
	global_load_dwordx4 v[182:185], v169, s[4:5]
	s_waitcnt vmcnt(3)
	v_add_u32_e32 v169, 16384, v117
	v_lshlrev_b32_e32 v142, 16, v170
	v_and_b32_e32 v143, 0xffff0000, v170
	v_lshlrev_b32_e32 v144, 16, v171
	v_and_b32_e32 v145, 0xffff0000, v171
	v_lshlrev_b32_e32 v146, 16, v172
	v_and_b32_e32 v147, 0xffff0000, v172
	v_lshlrev_b32_e32 v148, 16, v173
	v_and_b32_e32 v149, 0xffff0000, v173
	v_mul_f32_e32 v142, s68, v142
	v_mul_f32_e32 v143, s68, v143
	v_mul_f32_e32 v144, s68, v144
	v_mul_f32_e32 v145, s68, v145
	v_mul_f32_e32 v146, s68, v146
	v_mul_f32_e32 v147, s68, v147
	v_mul_f32_e32 v148, s68, v148
	v_mul_f32_e32 v149, s68, v149
	v_mul_f32_e32 v142, v142, v118
	v_mul_f32_e32 v143, v143, v119
	v_mul_f32_e32 v144, v144, v120
	v_mul_f32_e32 v145, v145, v121
	v_mul_f32_e32 v146, v146, v122
	v_mul_f32_e32 v147, v147, v123
	v_mul_f32_e32 v148, v148, v124
	v_mul_f32_e32 v149, v149, v125
	v_cvt_pk_bf16_f32 v150, v142, v143
	v_cvt_pk_bf16_f32 v151, v144, v145
	v_cvt_pk_bf16_f32 v152, v146, v147
	v_cvt_pk_bf16_f32 v153, v148, v149
	global_store_dwordx4 v169, v[150:153], s[6:7] offset:0
	s_nop 1
	s_waitcnt vmcnt(2)
	v_add_u32_e32 v169, 18432, v117
	v_lshlrev_b32_e32 v142, 16, v174
	v_and_b32_e32 v143, 0xffff0000, v174
	v_lshlrev_b32_e32 v144, 16, v175
	v_and_b32_e32 v145, 0xffff0000, v175
	v_lshlrev_b32_e32 v146, 16, v176
	v_and_b32_e32 v147, 0xffff0000, v176
	v_lshlrev_b32_e32 v148, 16, v177
	v_and_b32_e32 v149, 0xffff0000, v177
	v_mul_f32_e32 v142, s69, v142
	v_mul_f32_e32 v143, s69, v143
	v_mul_f32_e32 v144, s69, v144
	v_mul_f32_e32 v145, s69, v145
	v_mul_f32_e32 v146, s69, v146
	v_mul_f32_e32 v147, s69, v147
	v_mul_f32_e32 v148, s69, v148
	v_mul_f32_e32 v149, s69, v149
	v_mul_f32_e32 v142, v142, v118
	v_mul_f32_e32 v143, v143, v119
	v_mul_f32_e32 v144, v144, v120
	v_mul_f32_e32 v145, v145, v121
	v_mul_f32_e32 v146, v146, v122
	v_mul_f32_e32 v147, v147, v123
	v_mul_f32_e32 v148, v148, v124
	v_mul_f32_e32 v149, v149, v125
	v_cvt_pk_bf16_f32 v150, v142, v143
	v_cvt_pk_bf16_f32 v151, v144, v145
	v_cvt_pk_bf16_f32 v152, v146, v147
	v_cvt_pk_bf16_f32 v153, v148, v149
	global_store_dwordx4 v169, v[150:153], s[6:7] offset:0
	s_nop 1
	s_waitcnt vmcnt(1)
	v_add_u32_e32 v169, 20480, v117
	v_lshlrev_b32_e32 v142, 16, v178
	v_and_b32_e32 v143, 0xffff0000, v178
	v_lshlrev_b32_e32 v144, 16, v179
	v_and_b32_e32 v145, 0xffff0000, v179
	v_lshlrev_b32_e32 v146, 16, v180
	v_and_b32_e32 v147, 0xffff0000, v180
	v_lshlrev_b32_e32 v148, 16, v181
	v_and_b32_e32 v149, 0xffff0000, v181
	v_mul_f32_e32 v142, s70, v142
	v_mul_f32_e32 v143, s70, v143
	v_mul_f32_e32 v144, s70, v144
	v_mul_f32_e32 v145, s70, v145
	v_mul_f32_e32 v146, s70, v146
	v_mul_f32_e32 v147, s70, v147
	v_mul_f32_e32 v148, s70, v148
	v_mul_f32_e32 v149, s70, v149
	v_mul_f32_e32 v142, v142, v118
	v_mul_f32_e32 v143, v143, v119
	v_mul_f32_e32 v144, v144, v120
	v_mul_f32_e32 v145, v145, v121
	v_mul_f32_e32 v146, v146, v122
	v_mul_f32_e32 v147, v147, v123
	v_mul_f32_e32 v148, v148, v124
	v_mul_f32_e32 v149, v149, v125
	v_cvt_pk_bf16_f32 v150, v142, v143
	v_cvt_pk_bf16_f32 v151, v144, v145
	v_cvt_pk_bf16_f32 v152, v146, v147
	v_cvt_pk_bf16_f32 v153, v148, v149
	global_store_dwordx4 v169, v[150:153], s[6:7] offset:0
	s_nop 1
	s_waitcnt vmcnt(0)
	v_add_u32_e32 v169, 22528, v117
	v_lshlrev_b32_e32 v142, 16, v182
	v_and_b32_e32 v143, 0xffff0000, v182
	v_lshlrev_b32_e32 v144, 16, v183
	v_and_b32_e32 v145, 0xffff0000, v183
	v_lshlrev_b32_e32 v146, 16, v184
	v_and_b32_e32 v147, 0xffff0000, v184
	v_lshlrev_b32_e32 v148, 16, v185
	v_and_b32_e32 v149, 0xffff0000, v185
	v_mul_f32_e32 v142, s71, v142
	v_mul_f32_e32 v143, s71, v143
	v_mul_f32_e32 v144, s71, v144
	v_mul_f32_e32 v145, s71, v145
	v_mul_f32_e32 v146, s71, v146
	v_mul_f32_e32 v147, s71, v147
	v_mul_f32_e32 v148, s71, v148
	v_mul_f32_e32 v149, s71, v149
	v_mul_f32_e32 v142, v142, v118
	v_mul_f32_e32 v143, v143, v119
	v_mul_f32_e32 v144, v144, v120
	v_mul_f32_e32 v145, v145, v121
	v_mul_f32_e32 v146, v146, v122
	v_mul_f32_e32 v147, v147, v123
	v_mul_f32_e32 v148, v148, v124
	v_mul_f32_e32 v149, v149, v125
	v_cvt_pk_bf16_f32 v150, v142, v143
	v_cvt_pk_bf16_f32 v151, v144, v145
	v_cvt_pk_bf16_f32 v152, v146, v147
	v_cvt_pk_bf16_f32 v153, v148, v149
	global_store_dwordx4 v169, v[150:153], s[6:7] offset:0
	s_nop 1
	v_add_u32_e32 v169, 24576, v117
	global_load_dwordx4 v[170:173], v169, s[4:5]
	v_add_u32_e32 v169, 26624, v117
	global_load_dwordx4 v[174:177], v169, s[4:5]
	v_add_u32_e32 v169, 28672, v117
	global_load_dwordx4 v[178:181], v169, s[4:5]
	v_add_u32_e32 v169, 30720, v117
	global_load_dwordx4 v[182:185], v169, s[4:5]
	s_waitcnt vmcnt(3)
; DI u32x4 pack8(const float (&v)[8]) { u32x4 r; r.x = pk2(v[0], v[1]); r.y = pk2(v[2], v[3]); r.z = pk2(v[4], v[5]); r.w = pk2(v[6], v[7]); return r; }
; __global__ void __launch_bounds__(512, 2) fwd_megakernel(Args args) {
;     ...
;                 for (int r = 0; r < 4; ++r) { const int m = m0 + r * NGW; if (m < MTOK) {
;                     const f32x4 s0 = sv[r][0], s1 = sv[r][1], s2 = sv[r][2];
;                     const float r_ssd = rsqrtf((((s0.x + s0.y) + (s0.z + s0.w)) + ((s1.x + s1.y) + (s1.z + s1.w))) * (1.f / 512.f) + EPS);
;                     const float r_att = rsqrtf(((s2.x + s2.y) + (s2.z + s2.w)) * (1.f / 256.f) + EPS);
;                     float v[8]; unpack8(yv[r][0], v);
; #pragma unroll
;                     for (int i = 0; i < 8; ++i) v[i] = v[i] * r_ssd * nwA[i];
;                     *(u32x4*)(ycat + (size_t)m * DM + colA) = pack8(v);
;                     if (lane < 32) { unpack8(yv[r][1], v);
; #pragma unroll
;                         for (int i = 0; i < 8; ++i) v[i] = v[i] * r_att * nwB[i];
;                         *(u32x4*)(ycat + (size_t)m * DM + colB) = pack8(v); } } }
	v_add_u32_e32 v169, 24576, v117
	v_lshlrev_b32_e32 v142, 16, v170
	v_and_b32_e32 v143, 0xffff0000, v170
	v_lshlrev_b32_e32 v144, 16, v171
	v_and_b32_e32 v145, 0xffff0000, v171
	v_lshlrev_b32_e32 v146, 16, v172
	v_and_b32_e32 v147, 0xffff0000, v172
	v_lshlrev_b32_e32 v148, 16, v173
	v_and_b32_e32 v149, 0xffff0000, v173
	v_mul_f32_e32 v142, s72, v142
	v_mul_f32_e32 v143, s72, v143
	v_mul_f32_e32 v144, s72, v144
	v_mul_f32_e32 v145, s72, v145
	v_mul_f32_e32 v146, s72, v146
	v_mul_f32_e32 v147, s72, v147
	v_mul_f32_e32 v148, s72, v148
	v_mul_f32_e32 v149, s72, v149
	v_mul_f32_e32 v142, v142, v118
	v_mul_f32_e32 v143, v143, v119
	v_mul_f32_e32 v144, v144, v120
	v_mul_f32_e32 v145, v145, v121
	v_mul_f32_e32 v146, v146, v122
	v_mul_f32_e32 v147, v147, v123
	v_mul_f32_e32 v148, v148, v124
	v_mul_f32_e32 v149, v149, v125
	v_cvt_pk_bf16_f32 v150, v142, v143
	v_cvt_pk_bf16_f32 v151, v144, v145
	v_cvt_pk_bf16_f32 v152, v146, v147
	v_cvt_pk_bf16_f32 v153, v148, v149
	global_store_dwordx4 v169, v[150:153], s[6:7] offset:0
	s_nop 1
	s_waitcnt vmcnt(2)
	v_add_u32_e32 v169, 26624, v117
	v_lshlrev_b32_e32 v142, 16, v174
	v_and_b32_e32 v143, 0xffff0000, v174
	v_lshlrev_b32_e32 v144, 16, v175
	v_and_b32_e32 v145, 0xffff0000, v175
	v_lshlrev_b32_e32 v146, 16, v176
	v_and_b32_e32 v147, 0xffff0000, v176
	v_lshlrev_b32_e32 v148, 16, v177
	v_and_b32_e32 v149, 0xffff0000, v177
	v_mul_f32_e32 v142, s73, v142
	v_mul_f32_e32 v143, s73, v143
	v_mul_f32_e32 v144, s73, v144
	v_mul_f32_e32 v145, s73, v145
	v_mul_f32_e32 v146, s73, v146
	v_mul_f32_e32 v147, s73, v147
	v_mul_f32_e32 v148, s73, v148
	v_mul_f32_e32 v149, s73, v149
	v_mul_f32_e32 v142, v142, v118
	v_mul_f32_e32 v143, v143, v119
	v_mul_f32_e32 v144, v144, v120
	v_mul_f32_e32 v145, v145, v121
	v_mul_f32_e32 v146, v146, v122
	v_mul_f32_e32 v147, v147, v123
	v_mul_f32_e32 v148, v148, v124
	v_mul_f32_e32 v149, v149, v125
	v_cvt_pk_bf16_f32 v150, v142, v143
	v_cvt_pk_bf16_f32 v151, v144, v145
	v_cvt_pk_bf16_f32 v152, v146, v147
	v_cvt_pk_bf16_f32 v153, v148, v149
	global_store_dwordx4 v169, v[150:153], s[6:7] offset:0
	s_nop 1
	s_waitcnt vmcnt(1)
	v_add_u32_e32 v169, 28672, v117
	v_lshlrev_b32_e32 v142, 16, v178
	v_and_b32_e32 v143, 0xffff0000, v178
	v_lshlrev_b32_e32 v144, 16, v179
	v_and_b32_e32 v145, 0xffff0000, v179
	v_lshlrev_b32_e32 v146, 16, v180
	v_and_b32_e32 v147, 0xffff0000, v180
	v_lshlrev_b32_e32 v148, 16, v181
	v_and_b32_e32 v149, 0xffff0000, v181
	v_mul_f32_e32 v142, s74, v142
	v_mul_f32_e32 v143, s74, v143
	v_mul_f32_e32 v144, s74, v144
	v_mul_f32_e32 v145, s74, v145
	v_mul_f32_e32 v146, s74, v146
	v_mul_f32_e32 v147, s74, v147
	v_mul_f32_e32 v148, s74, v148
	v_mul_f32_e32 v149, s74, v149
	v_mul_f32_e32 v142, v142, v118
	v_mul_f32_e32 v143, v143, v119
	v_mul_f32_e32 v144, v144, v120
	v_mul_f32_e32 v145, v145, v121
	v_mul_f32_e32 v146, v146, v122
	v_mul_f32_e32 v147, v147, v123
	v_mul_f32_e32 v148, v148, v124
	v_mul_f32_e32 v149, v149, v125
	v_cvt_pk_bf16_f32 v150, v142, v143
	v_cvt_pk_bf16_f32 v151, v144, v145
	v_cvt_pk_bf16_f32 v152, v146, v147
	v_cvt_pk_bf16_f32 v153, v148, v149
	global_store_dwordx4 v169, v[150:153], s[6:7] offset:0
	s_nop 1
	s_waitcnt vmcnt(0)
	v_add_u32_e32 v169, 30720, v117
	v_lshlrev_b32_e32 v142, 16, v182
	v_and_b32_e32 v143, 0xffff0000, v182
	v_lshlrev_b32_e32 v144, 16, v183
	v_and_b32_e32 v145, 0xffff0000, v183
	v_lshlrev_b32_e32 v146, 16, v184
	v_and_b32_e32 v147, 0xffff0000, v184
	v_lshlrev_b32_e32 v148, 16, v185
	v_and_b32_e32 v149, 0xffff0000, v185
	v_mul_f32_e32 v142, s75, v142
	v_mul_f32_e32 v143, s75, v143
	v_mul_f32_e32 v144, s75, v144
	v_mul_f32_e32 v145, s75, v145
	v_mul_f32_e32 v146, s75, v146
	v_mul_f32_e32 v147, s75, v147
	v_mul_f32_e32 v148, s75, v148
	v_mul_f32_e32 v149, s75, v149
	v_mul_f32_e32 v142, v142, v118
	v_mul_f32_e32 v143, v143, v119
	v_mul_f32_e32 v144, v144, v120
	v_mul_f32_e32 v145, v145, v121
	v_mul_f32_e32 v146, v146, v122
	v_mul_f32_e32 v147, v147, v123
	v_mul_f32_e32 v148, v148, v124
	v_mul_f32_e32 v149, v149, v125
	v_cvt_pk_bf16_f32 v150, v142, v143
	v_cvt_pk_bf16_f32 v151, v144, v145
	v_cvt_pk_bf16_f32 v152, v146, v147
	v_cvt_pk_bf16_f32 v153, v148, v149
	global_store_dwordx4 v169, v[150:153], s[6:7] offset:0
	s_nop 1
	v_lshrrev_b32_e32 v162, 5, v116
	v_and_b32_e32 v164, 31, v116
	v_lshlrev_b32_e32 v164, 4, v164
	v_lshl_add_u32 v164, v162, 11, v164
	v_add_u32_e32 v164, 0x400, v164
	v_add_u32_e32 v169, 0, v164
	global_load_dwordx4 v[170:173], v169, s[4:5]
	v_add_u32_e32 v169, 4096, v164
	global_load_dwordx4 v[174:177], v169, s[4:5]
	v_add_u32_e32 v169, 8192, v164
	global_load_dwordx4 v[178:181], v169, s[4:5]
	v_add_u32_e32 v169, 12288, v164
	global_load_dwordx4 v[182:185], v169, s[4:5]
	v_add_u32_e32 v163, 0, v162
	v_lshlrev_b32_e32 v163, 2, v163
	ds_bpermute_b32 v168, v163, v160
	s_waitcnt vmcnt(3) lgkmcnt(0)
	v_add_u32_e32 v169, 0, v164
	v_lshlrev_b32_e32 v142, 16, v170
	v_and_b32_e32 v143, 0xffff0000, v170
	v_lshlrev_b32_e32 v144, 16, v171
	v_and_b32_e32 v145, 0xffff0000, v171
	v_lshlrev_b32_e32 v146, 16, v172
	v_and_b32_e32 v147, 0xffff0000, v172
	v_lshlrev_b32_e32 v148, 16, v173
	v_and_b32_e32 v149, 0xffff0000, v173
	v_mul_f32_e32 v142, v142, v168
	v_mul_f32_e32 v143, v143, v168
	v_mul_f32_e32 v144, v144, v168
	v_mul_f32_e32 v145, v145, v168
	v_mul_f32_e32 v146, v146, v168
	v_mul_f32_e32 v147, v147, v168
	v_mul_f32_e32 v148, v148, v168
	v_mul_f32_e32 v149, v149, v168
	v_mul_f32_e32 v142, v142, v126
	v_mul_f32_e32 v143, v143, v127
	v_mul_f32_e32 v144, v144, v128
	v_mul_f32_e32 v145, v145, v129
	v_mul_f32_e32 v146, v146, v130
	v_mul_f32_e32 v147, v147, v131
	v_mul_f32_e32 v148, v148, v132
	v_mul_f32_e32 v149, v149, v133
	v_cvt_pk_bf16_f32 v150, v142, v143
	v_cvt_pk_bf16_f32 v151, v144, v145
	v_cvt_pk_bf16_f32 v152, v146, v147
	v_cvt_pk_bf16_f32 v153, v148, v149
	global_store_dwordx4 v169, v[150:153], s[6:7] offset:0
	s_nop 1
	v_add_u32_e32 v163, 2, v162
	v_lshlrev_b32_e32 v163, 2, v163
	ds_bpermute_b32 v168, v163, v160
	s_waitcnt vmcnt(2) lgkmcnt(0)
; DI u32x4 pack8(const float (&v)[8]) { u32x4 r; r.x = pk2(v[0], v[1]); r.y = pk2(v[2], v[3]); r.z = pk2(v[4], v[5]); r.w = pk2(v[6], v[7]); return r; }
; __global__ void __launch_bounds__(512, 2) fwd_megakernel(Args args) {
;     ...
;                     if (lane < 32) { unpack8(yv[r][1], v);
; #pragma unroll
;                         for (int i = 0; i < 8; ++i) v[i] = v[i] * r_att * nwB[i];
;                         *(u32x4*)(ycat + (size_t)m * DM + colB) = pack8(v); } } }
	v_add_u32_e32 v169, 4096, v164
	v_lshlrev_b32_e32 v142, 16, v174
	v_and_b32_e32 v143, 0xffff0000, v174
	v_lshlrev_b32_e32 v144, 16, v175
	v_and_b32_e32 v145, 0xffff0000, v175
	v_lshlrev_b32_e32 v146, 16, v176
	v_and_b32_e32 v147, 0xffff0000, v176
	v_lshlrev_b32_e32 v148, 16, v177
	v_and_b32_e32 v149, 0xffff0000, v177
	v_mul_f32_e32 v142, v142, v168
	v_mul_f32_e32 v143, v143, v168
	v_mul_f32_e32 v144, v144, v168
	v_mul_f32_e32 v145, v145, v168
	v_mul_f32_e32 v146, v146, v168
	v_mul_f32_e32 v147, v147, v168
	v_mul_f32_e32 v148, v148, v168
	v_mul_f32_e32 v149, v149, v168
	v_mul_f32_e32 v142, v142, v126
	v_mul_f32_e32 v143, v143, v127
	v_mul_f32_e32 v144, v144, v128
	v_mul_f32_e32 v145, v145, v129
	v_mul_f32_e32 v146, v146, v130
	v_mul_f32_e32 v147, v147, v131
	v_mul_f32_e32 v148, v148, v132
	v_mul_f32_e32 v149, v149, v133
	v_cvt_pk_bf16_f32 v150, v142, v143
	v_cvt_pk_bf16_f32 v151, v144, v145
	v_cvt_pk_bf16_f32 v152, v146, v147
	v_cvt_pk_bf16_f32 v153, v148, v149
	global_store_dwordx4 v169, v[150:153], s[6:7] offset:0
	s_nop 1
	v_add_u32_e32 v163, 4, v162
	v_lshlrev_b32_e32 v163, 2, v163
	ds_bpermute_b32 v168, v163, v160
	s_waitcnt vmcnt(1) lgkmcnt(0)
	v_add_u32_e32 v169, 8192, v164
	v_lshlrev_b32_e32 v142, 16, v178
	v_and_b32_e32 v143, 0xffff0000, v178
	v_lshlrev_b32_e32 v144, 16, v179
	v_and_b32_e32 v145, 0xffff0000, v179
	v_lshlrev_b32_e32 v146, 16, v180
	v_and_b32_e32 v147, 0xffff0000, v180
	v_lshlrev_b32_e32 v148, 16, v181
	v_and_b32_e32 v149, 0xffff0000, v181
	v_mul_f32_e32 v142, v142, v168
	v_mul_f32_e32 v143, v143, v168
	v_mul_f32_e32 v144, v144, v168
	v_mul_f32_e32 v145, v145, v168
	v_mul_f32_e32 v146, v146, v168
	v_mul_f32_e32 v147, v147, v168
	v_mul_f32_e32 v148, v148, v168
	v_mul_f32_e32 v149, v149, v168
	v_mul_f32_e32 v142, v142, v126
	v_mul_f32_e32 v143, v143, v127
	v_mul_f32_e32 v144, v144, v128
	v_mul_f32_e32 v145, v145, v129
	v_mul_f32_e32 v146, v146, v130
	v_mul_f32_e32 v147, v147, v131
	v_mul_f32_e32 v148, v148, v132
	v_mul_f32_e32 v149, v149, v133
	v_cvt_pk_bf16_f32 v150, v142, v143
	v_cvt_pk_bf16_f32 v151, v144, v145
	v_cvt_pk_bf16_f32 v152, v146, v147
	v_cvt_pk_bf16_f32 v153, v148, v149
	global_store_dwordx4 v169, v[150:153], s[6:7] offset:0
	s_nop 1
	v_add_u32_e32 v163, 6, v162
	v_lshlrev_b32_e32 v163, 2, v163
	ds_bpermute_b32 v168, v163, v160
	s_waitcnt vmcnt(0) lgkmcnt(0)
	v_add_u32_e32 v169, 12288, v164
	v_lshlrev_b32_e32 v142, 16, v182
	v_and_b32_e32 v143, 0xffff0000, v182
	v_lshlrev_b32_e32 v144, 16, v183
	v_and_b32_e32 v145, 0xffff0000, v183
	v_lshlrev_b32_e32 v146, 16, v184
	v_and_b32_e32 v147, 0xffff0000, v184
	v_lshlrev_b32_e32 v148, 16, v185
	v_and_b32_e32 v149, 0xffff0000, v185
	v_mul_f32_e32 v142, v142, v168
	v_mul_f32_e32 v143, v143, v168
	v_mul_f32_e32 v144, v144, v168
	v_mul_f32_e32 v145, v145, v168
	v_mul_f32_e32 v146, v146, v168
	v_mul_f32_e32 v147, v147, v168
	v_mul_f32_e32 v148, v148, v168
	v_mul_f32_e32 v149, v149, v168
	v_mul_f32_e32 v142, v142, v126
	v_mul_f32_e32 v143, v143, v127
	v_mul_f32_e32 v144, v144, v128
	v_mul_f32_e32 v145, v145, v129
	v_mul_f32_e32 v146, v146, v130
	v_mul_f32_e32 v147, v147, v131
	v_mul_f32_e32 v148, v148, v132
	v_mul_f32_e32 v149, v149, v133
	v_cvt_pk_bf16_f32 v150, v142, v143
	v_cvt_pk_bf16_f32 v151, v144, v145
	v_cvt_pk_bf16_f32 v152, v146, v147
	v_cvt_pk_bf16_f32 v153, v148, v149
	global_store_dwordx4 v169, v[150:153], s[6:7] offset:0
	s_nop 1
	v_add_u32_e32 v169, 16384, v164
	global_load_dwordx4 v[170:173], v169, s[4:5]
	v_add_u32_e32 v169, 20480, v164
	global_load_dwordx4 v[174:177], v169, s[4:5]
	v_add_u32_e32 v169, 24576, v164
	global_load_dwordx4 v[178:181], v169, s[4:5]
	v_add_u32_e32 v169, 28672, v164
	global_load_dwordx4 v[182:185], v169, s[4:5]
	v_add_u32_e32 v163, 8, v162
	v_lshlrev_b32_e32 v163, 2, v163
	ds_bpermute_b32 v168, v163, v160
	s_waitcnt vmcnt(3) lgkmcnt(0)
	v_add_u32_e32 v169, 16384, v164
	v_lshlrev_b32_e32 v142, 16, v170
	v_and_b32_e32 v143, 0xffff0000, v170
	v_lshlrev_b32_e32 v144, 16, v171
	v_and_b32_e32 v145, 0xffff0000, v171
	v_lshlrev_b32_e32 v146, 16, v172
	v_and_b32_e32 v147, 0xffff0000, v172
	v_lshlrev_b32_e32 v148, 16, v173
	v_and_b32_e32 v149, 0xffff0000, v173
	v_mul_f32_e32 v142, v142, v168
	v_mul_f32_e32 v143, v143, v168
	v_mul_f32_e32 v144, v144, v168
	v_mul_f32_e32 v145, v145, v168
	v_mul_f32_e32 v146, v146, v168
	v_mul_f32_e32 v147, v147, v168
	v_mul_f32_e32 v148, v148, v168
	v_mul_f32_e32 v149, v149, v168
	v_mul_f32_e32 v142, v142, v126
	v_mul_f32_e32 v143, v143, v127
	v_mul_f32_e32 v144, v144, v128
	v_mul_f32_e32 v145, v145, v129
	v_mul_f32_e32 v146, v146, v130
	v_mul_f32_e32 v147, v147, v131
	v_mul_f32_e32 v148, v148, v132
	v_mul_f32_e32 v149, v149, v133
	v_cvt_pk_bf16_f32 v150, v142, v143
	v_cvt_pk_bf16_f32 v151, v144, v145
	v_cvt_pk_bf16_f32 v152, v146, v147
	v_cvt_pk_bf16_f32 v153, v148, v149
	global_store_dwordx4 v169, v[150:153], s[6:7] offset:0
	s_nop 1
	v_add_u32_e32 v163, 10, v162
	v_lshlrev_b32_e32 v163, 2, v163
	ds_bpermute_b32 v168, v163, v160
	s_waitcnt vmcnt(2) lgkmcnt(0)
; DI u32x4 pack8(const float (&v)[8]) { u32x4 r; r.x = pk2(v[0], v[1]); r.y = pk2(v[2], v[3]); r.z = pk2(v[4], v[5]); r.w = pk2(v[6], v[7]); return r; }
; __global__ void __launch_bounds__(512, 2) fwd_megakernel(Args args) {
;     ...
;                     if (lane < 32) { unpack8(yv[r][1], v);
; #pragma unroll
;                         for (int i = 0; i < 8; ++i) v[i] = v[i] * r_att * nwB[i];
;                         *(u32x4*)(ycat + (size_t)m * DM + colB) = pack8(v); } } }
	v_add_u32_e32 v169, 20480, v164
	v_lshlrev_b32_e32 v142, 16, v174
	v_and_b32_e32 v143, 0xffff0000, v174
	v_lshlrev_b32_e32 v144, 16, v175
	v_and_b32_e32 v145, 0xffff0000, v175
	v_lshlrev_b32_e32 v146, 16, v176
	v_and_b32_e32 v147, 0xffff0000, v176
	v_lshlrev_b32_e32 v148, 16, v177
	v_and_b32_e32 v149, 0xffff0000, v177
	v_mul_f32_e32 v142, v142, v168
	v_mul_f32_e32 v143, v143, v168
	v_mul_f32_e32 v144, v144, v168
	v_mul_f32_e32 v145, v145, v168
	v_mul_f32_e32 v146, v146, v168
	v_mul_f32_e32 v147, v147, v168
	v_mul_f32_e32 v148, v148, v168
	v_mul_f32_e32 v149, v149, v168
	v_mul_f32_e32 v142, v142, v126
	v_mul_f32_e32 v143, v143, v127
	v_mul_f32_e32 v144, v144, v128
	v_mul_f32_e32 v145, v145, v129
	v_mul_f32_e32 v146, v146, v130
	v_mul_f32_e32 v147, v147, v131
	v_mul_f32_e32 v148, v148, v132
	v_mul_f32_e32 v149, v149, v133
	v_cvt_pk_bf16_f32 v150, v142, v143
	v_cvt_pk_bf16_f32 v151, v144, v145
	v_cvt_pk_bf16_f32 v152, v146, v147
	v_cvt_pk_bf16_f32 v153, v148, v149
	global_store_dwordx4 v169, v[150:153], s[6:7] offset:0
	s_nop 1
	v_add_u32_e32 v163, 12, v162
	v_lshlrev_b32_e32 v163, 2, v163
	ds_bpermute_b32 v168, v163, v160
	s_waitcnt vmcnt(1) lgkmcnt(0)
	v_add_u32_e32 v169, 24576, v164
	v_lshlrev_b32_e32 v142, 16, v178
	v_and_b32_e32 v143, 0xffff0000, v178
	v_lshlrev_b32_e32 v144, 16, v179
	v_and_b32_e32 v145, 0xffff0000, v179
	v_lshlrev_b32_e32 v146, 16, v180
	v_and_b32_e32 v147, 0xffff0000, v180
	v_lshlrev_b32_e32 v148, 16, v181
	v_and_b32_e32 v149, 0xffff0000, v181
	v_mul_f32_e32 v142, v142, v168
	v_mul_f32_e32 v143, v143, v168
	v_mul_f32_e32 v144, v144, v168
	v_mul_f32_e32 v145, v145, v168
	v_mul_f32_e32 v146, v146, v168
	v_mul_f32_e32 v147, v147, v168
	v_mul_f32_e32 v148, v148, v168
	v_mul_f32_e32 v149, v149, v168
	v_mul_f32_e32 v142, v142, v126
	v_mul_f32_e32 v143, v143, v127
	v_mul_f32_e32 v144, v144, v128
	v_mul_f32_e32 v145, v145, v129
	v_mul_f32_e32 v146, v146, v130
	v_mul_f32_e32 v147, v147, v131
	v_mul_f32_e32 v148, v148, v132
	v_mul_f32_e32 v149, v149, v133
	v_cvt_pk_bf16_f32 v150, v142, v143
	v_cvt_pk_bf16_f32 v151, v144, v145
	v_cvt_pk_bf16_f32 v152, v146, v147
	v_cvt_pk_bf16_f32 v153, v148, v149
	global_store_dwordx4 v169, v[150:153], s[6:7] offset:0
	s_nop 1
	v_add_u32_e32 v163, 14, v162
	v_lshlrev_b32_e32 v163, 2, v163
	ds_bpermute_b32 v168, v163, v160
	s_waitcnt vmcnt(0) lgkmcnt(0)
	v_add_u32_e32 v169, 28672, v164
	v_lshlrev_b32_e32 v142, 16, v182
	v_and_b32_e32 v143, 0xffff0000, v182
	v_lshlrev_b32_e32 v144, 16, v183
	v_and_b32_e32 v145, 0xffff0000, v183
	v_lshlrev_b32_e32 v146, 16, v184
	v_and_b32_e32 v147, 0xffff0000, v184
	v_lshlrev_b32_e32 v148, 16, v185
	v_and_b32_e32 v149, 0xffff0000, v185
	v_mul_f32_e32 v142, v142, v168
	v_mul_f32_e32 v143, v143, v168
	v_mul_f32_e32 v144, v144, v168
	v_mul_f32_e32 v145, v145, v168
	v_mul_f32_e32 v146, v146, v168
	v_mul_f32_e32 v147, v147, v168
	v_mul_f32_e32 v148, v148, v168
	v_mul_f32_e32 v149, v149, v168
	v_mul_f32_e32 v142, v142, v126
	v_mul_f32_e32 v143, v143, v127
	v_mul_f32_e32 v144, v144, v128
	v_mul_f32_e32 v145, v145, v129
	v_mul_f32_e32 v146, v146, v130
	v_mul_f32_e32 v147, v147, v131
	v_mul_f32_e32 v148, v148, v132
	v_mul_f32_e32 v149, v149, v133
	v_cvt_pk_bf16_f32 v150, v142, v143
	v_cvt_pk_bf16_f32 v151, v144, v145
	v_cvt_pk_bf16_f32 v152, v146, v147
	v_cvt_pk_bf16_f32 v153, v148, v149
	global_store_dwordx4 v169, v[150:153], s[6:7] offset:0
	s_nop 1
	v_readlane_b32 s76, v251, 57
	v_readlane_b32 s77, v251, 58
	v_readlane_b32 s52, v251, 61
	v_readlane_b32 s78, v253, 42
	v_readlane_b32 s53, v251, 62
	v_readlane_b32 s72, v251, 59
	v_readlane_b32 s79, v253, 43
	v_readlane_b32 s51, v251, 63
	v_readlane_b32 s54, v251, 0
	v_readlane_b32 s73, v251, 60
	s_mul_i32 s55, s82, 24
	v_readlane_b32 s74, v253, 27
	v_readlane_b32 s75, v253, 28
	v_readlane_b32 s79, v253, 29
	v_readlane_b32 s83, v253, 30
	v_readlane_b32 s53, v253, 26
	s_nop 4
	s_branch .LBB0_1129

; __device__ __forceinline__ void xcd_barrier(const XcdBarrier& b) {
;     ...
;     if (threadIdx.x == 0) {
;         unsigned* bar = b.bar;
;         __builtin_amdgcn_s_waitcnt(0);
;         unsigned nloc = b.st[0], nx = b.st[1];
;         if (nloc == 0u) { xcd_barrier_complete(bar, b.x, nloc, nx); b.st[0] = nloc; b.st[1] = nx; }
.Lfb8_slow:
	v_readlane_b32 s3, v253, 23
	s_waitcnt vmcnt(0) expcnt(0) lgkmcnt(0)
	s_and_b32 s2, s2, 15
	v_mov_b32_e32 v0, s3
	ds_read_b32 v2, v0
	v_readlane_b32 s3, v253, 24
	s_waitcnt lgkmcnt(0)
	v_cmp_ne_u32_e32 vcc, 0, v2
	v_mov_b32_e32 v0, s3
	ds_read_b32 v0, v0
	s_cbranch_vccnz .LBB0_1160
	s_mov_b32 s3, 1
	s_branch .LBB0_1148
.LBB0_1132:
	s_or_b64 exec, exec, s[4:5]
